# scan: staging waves keep the 18 DMA source addresses in registers; per step only m0 + issue, addresses advanced after the burst
# speedup vs baseline: 1.0191x; 1.0014x over previous
.LBB0_157:
	s_and_b32 s19, s37, 0xffffffc0
	v_or_b32_e32 v3, s19, v160
	v_readlane_b32 s8, v254, 48
	v_ashrrev_i32_e32 v4, 4, v3
	s_and_b32 s6, s80, 1
	s_lshl_b32 s7, s8, 4
	v_xor_b32_e32 v0, v4, v160
	s_lshl_b32 s16, s6, 6
	s_and_b32 s17, s7, 48
	s_lshl_b32 s18, s6, 8
	v_lshlrev_b32_e32 v14, 4, v160
	v_lshlrev_b32_e32 v2, 8, v4
	v_lshlrev_b32_e32 v0, 4, v0
	s_movk_i32 s7, 0xf0
	s_movk_i32 s6, 0x70
	v_and_or_b32 v0, v0, s7, v2
	v_lshlrev_b32_e32 v2, 4, v3
	v_bitop3_b32 v15, v3, s6, v14 bitop3:0x48
	v_add_u32_e32 v3, 0x200, v3
	v_ashrrev_i32_e32 v7, 4, v3
	v_xor_b32_e32 v6, v7, v160
	v_and_b32_e32 v5, 0xf0, v14
	s_movk_i32 s23, 0xff80
	v_lshlrev_b32_e32 v8, 8, v7
	v_lshlrev_b32_e32 v6, 4, v6
	v_lshlrev_b32_e32 v3, 4, v3
	s_ashr_i32 s9, s80, 3
	v_lshl_or_b32 v4, v4, 9, v5
	v_and_or_b32 v6, v6, s7, v8
	v_and_or_b32 v8, v3, s23, v15
	v_lshl_or_b32 v10, v7, 9, v5
	v_lshlrev_b32_e32 v3, 8, v145
	v_xor_b32_e32 v5, v144, v145
	s_add_u32 s14, s2, s18
	v_lshl_or_b32 v58, v5, 4, v3
	v_bitop3_b32 v5, v144, v145, 4 bitop3:0x36
	s_addc_u32 s15, s3, 0
	s_lshl_b32 s8, s8, 10
	s_lshl_b64 s[6:7], s[0:1], 20
	v_lshl_or_b32 v59, v5, 4, v3
	v_bitop3_b32 v5, v144, v145, 8 bitop3:0x36
	s_add_u32 s12, s2, s6
	v_lshl_or_b32 v60, v5, 4, v3
	v_bitop3_b32 v5, v144, v145, 12 bitop3:0x36
	s_addc_u32 s13, s3, s7
	v_lshl_or_b32 v61, v5, 4, v3
	v_lshrrev_b32_e32 v5, 1, v145
	s_add_u32 s10, s12, 0x17c00000
	v_lshlrev_b32_e32 v3, 7, v145
	v_xor_b32_e32 v7, v144, v5
	s_addc_u32 s11, s13, 0
	v_lshl_or_b32 v55, v7, 4, v3
	v_lshl_add_u64 v[12:13], s[10:11], 0, v[0:1]
	s_add_i32 s20, s8, 0
	v_mov_b32_e32 v7, v1
	s_mov_b32 s21, m0
	s_mov_b32 m0, s20
	s_nop 0
	global_load_lds_dwordx4 v[12:13], off
	s_mov_b32 m0, s21
	v_lshl_add_u64 v[12:13], s[10:11], 0, v[6:7]
	s_add_i32 s10, s20, 0x2000
	s_mov_b32 s11, m0
	s_mov_b32 m0, s10
	s_nop 0
	global_load_lds_dwordx4 v[12:13], off
	s_mov_b32 m0, s11
	s_add_u32 s10, s12, 0x15c00000
	s_addc_u32 s11, s13, 0
	v_lshl_add_u64 v[12:13], s[10:11], 0, v[0:1]
	s_add_i32 s21, s20, 0x4000
	s_mov_b32 s22, m0
	s_mov_b32 m0, s21
	s_nop 0
	global_load_lds_dwordx4 v[12:13], off
	s_mov_b32 m0, s22
	v_lshl_add_u64 v[12:13], s[10:11], 0, v[6:7]
	s_add_i32 s10, s20, 0x6000
	v_bitop3_b32 v5, v144, v5, 4 bitop3:0x36
	s_mov_b32 s11, m0
	s_mov_b32 m0, s10
	s_nop 0
	global_load_lds_dwordx4 v[12:13], off
	s_mov_b32 m0, s11
	s_add_u32 s10, s12, 0x19c00000
	v_and_or_b32 v2, v2, s23, v15
	v_lshl_or_b32 v54, v5, 4, v3
	s_addc_u32 s11, s13, 0
	v_mov_b32_e32 v3, v1
	v_lshl_add_u64 v[12:13], s[10:11], 0, v[2:3]
	s_add_i32 s12, s20, 0x8000
	s_mov_b32 s13, m0
	s_mov_b32 m0, s12
	s_nop 0
	global_load_lds_dwordx4 v[12:13], off
	s_mov_b32 m0, s13
	v_mov_b32_e32 v9, v1
	v_lshl_add_u64 v[8:9], s[10:11], 0, v[8:9]
	s_add_i32 s10, s20, 0xa000
	s_mov_b32 s11, m0
	s_mov_b32 m0, s10
	s_nop 0
	global_load_lds_dwordx4 v[8:9], off
	s_mov_b32 m0, s11
	s_lshl_b64 s[10:11], s[0:1], 19
	s_add_u32 s12, s2, s10
	s_addc_u32 s13, s3, s11
	v_lshl_add_u64 v[2:3], s[12:13], 0, v[2:3]
	s_mov_b64 s[12:13], 0x1bc00000
	v_lshl_add_u64 v[2:3], v[2:3], 0, s[12:13]
	s_add_i32 s12, s20, 0xc000
	s_mov_b32 s13, m0
	s_mov_b32 m0, s12
	s_nop 0
	global_load_lds_dwordx4 v[2:3], off
	s_mov_b32 m0, s13
	s_lshl_b64 s[12:13], s[0:1], 21
	s_add_u32 s1, s14, s12
	s_addc_u32 s15, s15, s13
	s_add_u32 s14, s1, 0x1c00000
	s_addc_u32 s15, s15, 0
	v_mov_b32_e32 v5, v1
	v_lshl_add_u64 v[2:3], s[14:15], 0, v[4:5]
	v_mov_b32_e32 v11, v1
	s_add_i32 s1, s20, 0xe000
	s_mov_b32 s21, m0
	s_mov_b32 m0, s1
	s_nop 0
	global_load_lds_dwordx4 v[2:3], off
	s_mov_b32 m0, s21
	v_lshl_add_u64 v[2:3], s[14:15], 0, v[10:11]
	s_add_i32 s20, s20, 0x10000
	s_mov_b32 s1, m0
	s_mov_b32 m0, s20
	s_nop 0
	global_load_lds_dwordx4 v[2:3], off
	s_mov_b32 m0, s1
	v_or_b32_e32 v2, s17, v145
	s_mul_hi_i32 s1, s9, 0x1800000
	s_mul_i32 s9, s9, 0x1800000
	v_lshlrev_b32_e32 v57, 2, v2
	v_bfe_u32 v2, v158, 4, 2
	s_add_u32 s14, s9, 0x9c00800
	v_mul_hi_u32_u24_e32 v3, 0x6000, v2
	v_mul_u32_u24_e32 v2, 0x6000, v2
	s_addc_u32 s15, s1, 0
	v_or_b32_e32 v2, s14, v2
	s_lshl_b32 s14, s80, 7
	v_or_b32_e32 v39, s15, v3
	s_and_b32 s14, s14, 0x300
	s_or_b32 s15, s16, s17
	s_or_b32 s12, s12, s18
	s_add_u32 s12, s12, 0x1c08000
	s_addc_u32 s13, s13, 0
	s_add_u32 s10, s10, 0x1bc02000
	v_or_b32_e32 v3, s15, v145
	v_lshl_add_u64 v[40:41], s[12:13], 0, v[10:11]
	v_lshl_add_u64 v[42:43], s[12:13], 0, v[4:5]
	s_addc_u32 s11, s11, 0
	s_lshl_b32 s12, s37, 4
	v_lshlrev_b32_e32 v36, 1, v3
	s_and_b32 s12, s12, 0xfffffc00
	v_or3_b32 v38, v2, s14, v36
	v_or_b32_e32 v2, s12, v14
	v_and_or_b32 v2, v2, s23, v15
	v_mov_b32_e32 v3, v1
	v_lshl_add_u64 v[44:45], s[10:11], 0, v[2:3]
	s_add_u32 s10, s6, 0x19c04000
	s_addc_u32 s11, s7, 0
	s_addk_i32 s19, 0x200
	v_or_b32_e32 v4, s19, v160
	v_lshlrev_b32_e32 v4, 4, v4
	s_waitcnt vmcnt(0)
	v_and_or_b32 v4, v4, s23, v15
	v_lshl_add_u64 v[48:49], s[10:11], 0, v[2:3]
	v_mov_b32_e32 v2, v1
	v_lshl_add_u64 v[46:47], s[10:11], 0, v[4:5]
	v_lshl_add_u64 v[50:51], s[6:7], 0, v[6:7]
	v_lshl_add_u64 v[52:53], s[6:7], 0, v[0:1]
	v_mov_b32_e32 v0, v1
	v_mov_b64_e32 v[34:35], v[2:3]
	v_mov_b64_e32 v[30:31], v[2:3]
	v_mov_b64_e32 v[26:27], v[2:3]
	v_mov_b64_e32 v[22:23], v[2:3]
	v_mov_b64_e32 v[18:19], v[2:3]
	v_mov_b64_e32 v[10:11], v[2:3]
	v_mov_b64_e32 v[6:7], v[2:3]
	v_mov_b64_e32 v[14:15], v[2:3]
	v_lshlrev_b32_e32 v56, 10, v144
	s_mov_b32 s11, 0
	s_mov_b32 s10, 0
	v_mov_b64_e32 v[32:33], v[0:1]
	v_mov_b64_e32 v[28:29], v[0:1]
	v_mov_b64_e32 v[24:25], v[0:1]
	v_mov_b64_e32 v[20:21], v[0:1]
	v_mov_b64_e32 v[16:17], v[0:1]
	v_mov_b64_e32 v[8:9], v[0:1]
	v_mov_b64_e32 v[4:5], v[0:1]
	v_mov_b64_e32 v[12:13], v[0:1]
	s_and_b64 vcc, exec, s[4:5]
	s_cbranch_vccz .Lscan_setup_done
	s_mov_b64 s[12:13], 0x17c04000
	s_mov_b64 s[14:15], 0x15c04000
	v_lshl_add_u64 v[100:101], s[2:3], 0, v[52:53]
	v_lshl_add_u64 v[102:103], s[2:3], 0, v[50:51]
	v_lshl_add_u64 v[62:63], v[100:101], 0, s[12:13]
	v_lshl_add_u64 v[64:65], v[102:103], 0, s[12:13]
	v_lshl_add_u64 v[66:67], v[100:101], 0, s[14:15]
	v_lshl_add_u64 v[68:69], v[102:103], 0, s[14:15]
	v_lshl_add_u64 v[70:71], s[2:3], 0, v[48:49]
	v_lshl_add_u64 v[72:73], s[2:3], 0, v[46:47]
	v_lshl_add_u64 v[74:75], s[2:3], 0, v[44:45]
	v_lshl_add_u64 v[76:77], s[2:3], 0, v[42:43]
	v_lshl_add_u64 v[78:79], s[2:3], 0, v[40:41]
	s_mov_b32 s12, 0xfffff000
	s_mov_b32 s13, -1
	s_mov_b32 s14, 0xffffe000
	s_mov_b32 s15, -1
	v_lshl_add_u64 v[80:81], v[62:63], 0, s[12:13]
	v_lshl_add_u64 v[82:83], v[64:65], 0, s[12:13]
	v_lshl_add_u64 v[86:87], v[66:67], 0, s[12:13]
	v_lshl_add_u64 v[88:89], v[68:69], 0, s[12:13]
	v_lshl_add_u64 v[90:91], v[70:71], 0, s[12:13]
	v_lshl_add_u64 v[92:93], v[72:73], 0, s[12:13]
	v_lshl_add_u64 v[94:95], v[74:75], 0, s[12:13]
	v_lshl_add_u64 v[96:97], v[76:77], 0, s[14:15]
	v_lshl_add_u64 v[98:99], v[78:79], 0, s[14:15]
.Lscan_setup_done:
	s_waitcnt vmcnt(0) lgkmcnt(0)
	s_barrier
	s_branch .LBB0_159

.LBB0_159:
	s_and_b64 vcc, exec, s[4:5]
	s_cbranch_vccz .Lscan_nostage
	s_setprio 3
	s_xor_b32 s6, s11, 1
	s_mul_i32 s6, s6, 0x12000
	s_add_i32 s6, s6, s8
	s_mov_b32 s7, m0
	s_add_i32 m0, s6, 0x0
	s_nop 0
	global_load_lds_dwordx4 v[62:63], off
	s_add_i32 m0, s6, 0x2000
	s_nop 0
	global_load_lds_dwordx4 v[64:65], off
	s_add_i32 m0, s6, 0x4000
	s_nop 0
	global_load_lds_dwordx4 v[66:67], off
	s_add_i32 m0, s6, 0x6000
	s_nop 0
	global_load_lds_dwordx4 v[68:69], off
	s_add_i32 m0, s6, 0x8000
	s_nop 0
	global_load_lds_dwordx4 v[70:71], off
	s_add_i32 m0, s6, 0xa000
	s_nop 0
	global_load_lds_dwordx4 v[72:73], off
	s_add_i32 m0, s6, 0xc000
	s_nop 0
	global_load_lds_dwordx4 v[74:75], off
	s_add_i32 m0, s6, 0xe000
	s_nop 0
	global_load_lds_dwordx4 v[76:77], off
	s_add_i32 m0, s6, 0x10000
	s_nop 0
	global_load_lds_dwordx4 v[78:79], off
	s_add_i32 s6, s6, 0xfffff000
	s_add_i32 m0, s6, 0x0
	s_nop 0
	global_load_lds_dwordx4 v[80:81], off
	s_add_i32 m0, s6, 0x2000
	s_nop 0
	global_load_lds_dwordx4 v[82:83], off
	s_add_i32 m0, s6, 0x4000
	s_nop 0
	global_load_lds_dwordx4 v[86:87], off
	s_add_i32 m0, s6, 0x6000
	s_nop 0
	global_load_lds_dwordx4 v[88:89], off
	s_add_i32 m0, s6, 0x8000
	s_nop 0
	global_load_lds_dwordx4 v[90:91], off
	s_add_i32 m0, s6, 0xa000
	s_nop 0
	global_load_lds_dwordx4 v[92:93], off
	s_add_i32 m0, s6, 0xc000
	s_nop 0
	global_load_lds_dwordx4 v[94:95], off
	s_add_i32 m0, s6, 0xe000
	s_nop 0
	global_load_lds_dwordx4 v[96:97], off
	s_add_i32 m0, s6, 0x10000
	s_nop 0
	global_load_lds_dwordx4 v[98:99], off
	s_mov_b32 m0, s7
	s_setprio 0
	s_mov_b64 s[12:13], 0x4000
	s_mov_b64 s[14:15], 0x8000
	v_lshl_add_u64 v[62:63], v[62:63], 0, s[12:13]
	v_lshl_add_u64 v[64:65], v[64:65], 0, s[12:13]
	v_lshl_add_u64 v[66:67], v[66:67], 0, s[12:13]
	v_lshl_add_u64 v[68:69], v[68:69], 0, s[12:13]
	v_lshl_add_u64 v[70:71], v[70:71], 0, s[12:13]
	v_lshl_add_u64 v[72:73], v[72:73], 0, s[12:13]
	v_lshl_add_u64 v[74:75], v[74:75], 0, s[34:35]
	v_lshl_add_u64 v[76:77], v[76:77], 0, s[14:15]
	v_lshl_add_u64 v[78:79], v[78:79], 0, s[14:15]
	v_lshl_add_u64 v[80:81], v[80:81], 0, s[12:13]
	v_lshl_add_u64 v[82:83], v[82:83], 0, s[12:13]
	v_lshl_add_u64 v[86:87], v[86:87], 0, s[12:13]
	v_lshl_add_u64 v[88:89], v[88:89], 0, s[12:13]
	v_lshl_add_u64 v[90:91], v[90:91], 0, s[12:13]
	v_lshl_add_u64 v[92:93], v[92:93], 0, s[12:13]
	v_lshl_add_u64 v[94:95], v[94:95], 0, s[34:35]
	v_lshl_add_u64 v[96:97], v[96:97], 0, s[14:15]
	v_lshl_add_u64 v[98:99], v[98:99], 0, s[14:15]
